# row-panel group barriers also after merge (both layers); barrier in front of FF1 additionally waits for the merges whose gate/AB rows F overlays
# speedup vs baseline: 1.0272x; 1.0147x over previous
.Lrp_done:
	s_cmp_eq_u32 s14, 11
	s_cbranch_scc1 .LBB0_681
	s_cmp_ge_i32 s17, s15
	s_cbranch_scc1 .LBB0_681
	v_readlane_b32 s99, v255, 59
	s_lshr_b32 s98, 0x160180, s14
	s_and_b32 s98, s98, s99
	s_bitcmp1_b32 s98, 0
	s_cbranch_scc0 .Lgg_no
	s_waitcnt vmcnt(0)
	s_barrier
	s_and_saveexec_b64 s[2:3], s[86:87]
	s_cbranch_execz .Lgg_join
	v_readlane_b32 s6, v253, 55
	s_and_b32 s7, s6, 7
	s_lshl_b32 s7, s7, 3
	s_bfe_u32 s6, s6, 0x30003
	s_add_i32 s6, s6, s7
	s_lshl_b32 s7, s6, 8
	s_add_i32 s7, s7, 0x4040
	s_cmp_eq_u32 s14, 18
	s_cselect_b32 s8, 4, 0
	s_cmp_eq_u32 s14, 20
	s_cselect_b32 s8, 8, s8
	s_cmp_eq_u32 s14, 7
	s_cselect_b32 s8, 12, s8
	s_cmp_eq_u32 s14, 17
	s_cselect_b32 s8, 16, s8
	s_add_i32 s8, s7, s8
	v_mov_b32_e32 v20, s8
	s_lshl_b32 s9, s6, 2
	s_and_b32 s9, s9, 63
	s_lshl_b32 s9, s9, 8
	s_add_i32 s9, s9, 0x404c
	s_cmp_eq_u32 s14, 18
	s_cselect_b32 s10, 4, 0
	s_add_i32 s9, s9, s10
	s_cmp_eq_u32 s14, 8
	s_cselect_b32 s10, 1, 0
	s_cmp_eq_u32 s14, 18
	s_cselect_b32 s10, 1, s10
	s_cmp_lt_u32 s6, 48
	s_cselect_b32 s10, s10, 0
	s_cmp_eq_u32 s10, 1
	s_cselect_b32 s9, s9, s8
	s_cselect_b32 s10, 0x100, 0
	v_mov_b32_e32 v21, s9
	s_add_i32 s9, s9, s10
	v_mov_b32_e32 v23, s9
	s_add_i32 s9, s9, s10
	v_mov_b32_e32 v24, s9
	s_add_i32 s9, s9, s10
	v_mov_b32_e32 v25, s9
	s_mov_b32 s58, 0
	global_atomic_add v20, v202, s[12:13]
.Lgg_spin:
	global_load_dword v22, v20, s[12:13] sc1
	global_load_dword v26, v21, s[12:13] sc1
	global_load_dword v27, v23, s[12:13] sc1
	global_load_dword v28, v24, s[12:13] sc1
	global_load_dword v29, v25, s[12:13] sc1
	s_waitcnt vmcnt(0)
	v_min_u32_e32 v22, v22, v26
	v_min3_u32 v22, v22, v27, v28
	v_min_u32_e32 v22, v22, v29
	v_cmp_gt_u32_e32 vcc, 4, v22
	s_cbranch_vccz .Lgg_done
	s_sleep 1
	s_add_i32 s58, s58, 1
	s_cmp_lt_u32 s58, 0x40001
	s_cbranch_scc1 .Lgg_spin
